# diff-attn unit prologue: Q staging loads batched (one wait), second K tile loads hoisted next to the first K/V tile loads
# baseline (speedup 1.0000x reference)
.LBB0_301:
	s_or_b64 exec, exec, s[2:3]
	s_ashr_i32 s12, s14, 3
	s_ashr_i32 s13, s12, 31
	s_lshl_b64 s[2:3], s[12:13], 13
	s_lshl_b32 s13, s22, 7
	v_and_b32_e32 v4, 31, v159
	s_ashr_i32 s4, s13, 31
	v_and_b32_e32 v0, 63, v159
	s_add_u32 s5, s2, s13
	v_or_b32_e32 v158, s17, v4
	v_lshlrev_b32_e32 v0, 4, v0
	v_or_b32_e32 v146, s5, v158
	v_mov_b64_e32 v[6:7], s[48:49]
	v_add_u32_e32 v162, s16, v0
	s_addc_u32 s14, s3, s4
	v_mad_u64_u32 v[0:1], s[4:5], v146, s53, v[6:7]
	v_mad_i32_i24 v1, s14, v216, v1
	s_lshl_b32 s90, s21, 8
	v_bfe_u32 v5, v159, 5, 1
	v_lshl_add_u64 v[0:1], v[0:1], 0, s[90:91]
	v_lshl_add_u64 v[0:1], s[6:7], 1, v[0:1]
	v_lshlrev_b32_e32 v168, 4, v5
	v_lshl_add_u64 v[8:9], v[0:1], 0, v[168:169]
	global_load_dwordx4 v[112:115], v[8:9], off
	global_load_dwordx4 v[116:119], v[8:9], off offset:32
	global_load_dwordx4 v[120:123], v[8:9], off offset:64
	global_load_dwordx4 v[124:127], v[8:9], off offset:96
	v_ashrrev_i32_e32 v128, 3, v159
	v_ashrrev_i32_e32 v129, 31, v128
	v_ashrrev_i32_e32 v130, 4, v159
	v_mov_b32_e32 v23, v169
	v_ashrrev_i32_e32 v131, 31, v130
	s_or_b32 s23, s13, s17
	v_lshlrev_b32_e32 v157, 2, v5
	v_or_b32_e32 v5, s23, v4
	s_cmpk_gt_i32 s23, 0x627
	v_mov_b32_e32 v147, s14
	s_waitcnt vmcnt(0)
	ds_write_b128 v162, v[112:115]
	ds_write_b128 v162, v[116:119] offset:1024
	ds_write_b128 v162, v[120:123] offset:2048
	ds_write_b128 v162, v[124:127] offset:3072
	v_lshlrev_b32_e32 v8, 4, v159
	v_and_b32_e32 v22, 0x70, v8
	v_lshl_add_u64 v[0:1], s[2:3], 0, v[128:129]
	v_mad_u64_u32 v[2:3], s[4:5], v0, s53, v[6:7]
	v_mad_i32_i24 v3, v1, s53, v3
	v_lshl_add_u64 v[0:1], v[2:3], 0, s[90:91]
	v_lshl_add_u64 v[2:3], v[0:1], 0, v[22:23]
	v_lshl_add_u64 v[0:1], s[2:3], 0, v[130:131]
	v_mad_u64_u32 v[6:7], s[2:3], v0, s53, v[6:7]
	v_mad_i32_i24 v7, v1, s53, v7
	s_movk_i32 s2, 0x90
	v_lshl_add_u64 v[0:1], v[6:7], 0, s[90:91]
	v_and_b32_e32 v6, 0xf0, v8
	v_mov_b32_e32 v7, v169
	v_mul_lo_u32 v23, v128, s2
	s_movk_i32 s2, 0x140
	v_mad_u64_u32 v[132:133], s[2:3], v130, s2, v[6:7]
	v_lshl_add_u64 v[0:1], v[0:1], 0, v[6:7]
	s_movk_i32 s2, 0x1000
	v_add_co_u32_e32 v14, vcc, s2, v0
	s_mov_b32 s2, 0x31000
	s_nop 0
	v_addc_co_u32_e32 v15, vcc, 0, v1, vcc
	global_load_dwordx4 v[6:9], v[2:3], off offset:2048
	global_load_dwordx4 v[10:13], v[2:3], off offset:2176
	v_add_co_u32_e32 v18, vcc, s2, v0
	global_load_dwordx4 v[14:17], v[14:15], off
	s_nop 0
	v_addc_co_u32_e32 v19, vcc, 0, v1, vcc
	global_load_dwordx4 v[18:21], v[18:19], off
	v_add_co_u32_e32 v56, vcc, 0x60000, v2
	s_nop 1
	v_addc_co_u32_e32 v57, vcc, 0, v3, vcc
	global_load_dwordx4 v[48:51], v[56:57], off offset:2048
	global_load_dwordx4 v[52:55], v[56:57], off offset:2176
	v_add3_u32 v163, v23, v22, 0
	s_mov_b32 s2, 0x60000
	v_add_u32_e32 v164, 0, v132
	s_cselect_b64 s[4:5], -1, 0
	s_cmpk_lt_i32 s23, 0x628
	v_sub_u32_e32 v129, v5, v157
	s_waitcnt vmcnt(5)
	ds_write_b128 v163, v[6:9]
	s_waitcnt vmcnt(4)
	ds_write_b128 v163, v[10:13] offset:9216
	s_waitcnt vmcnt(3)
	ds_write_b128 v164, v[14:17] offset:36864
	s_waitcnt vmcnt(2)
	ds_write_b128 v164, v[18:21] offset:47104
	v_readlane_b32 s2, v254, 57
	s_waitcnt vmcnt(1)
	ds_write_b128 v163, v[48:51] offset:18432
	s_waitcnt vmcnt(0)
	ds_write_b128 v163, v[52:55] offset:27648
	v_mov_b32_e32 v6, s2
	s_waitcnt lgkmcnt(0)
	s_barrier
	ds_read_b32 v165, v6
	s_mov_b64 s[2:3], -1
	s_cbranch_scc0 .LBB0_303
	s_add_i32 s2, 0, 0x18000
	v_lshl_add_u32 v5, v129, 2, s2
	ds_read2_b32 v[6:7], v5 offset0:127 offset1:128
	ds_read2_b32 v[8:9], v5 offset0:125 offset1:126
	ds_read2_b32 v[10:11], v5 offset0:119 offset1:120
	ds_read2_b32 v[12:13], v5 offset0:117 offset1:118
	ds_read2_b32 v[14:15], v5 offset0:95 offset1:96
	ds_read2_b32 v[32:33], v5 offset0:93 offset1:94
	ds_read2_b32 v[34:35], v5 offset0:87 offset1:88
	ds_read2_b32 v[36:37], v5 offset0:85 offset1:86
	ds_read2_b32 v[16:17], v5 offset0:111 offset1:112
	ds_read2_b32 v[18:19], v5 offset0:109 offset1:110
	ds_read2_b32 v[20:21], v5 offset0:103 offset1:104
	ds_read2_b32 v[22:23], v5 offset0:101 offset1:102
	ds_read2_b32 v[38:39], v5 offset0:79 offset1:80
	ds_read2_b32 v[40:41], v5 offset0:77 offset1:78
	ds_read2_b32 v[42:43], v5 offset0:71 offset1:72
	ds_read2_b32 v[56:57], v5 offset0:69 offset1:70
	s_mov_b64 s[2:3], 0
	s_waitcnt lgkmcnt(4)
	v_mov_b32_e32 v31, v22
	v_mov_b32_e32 v30, v23
	v_mov_b32_e32 v29, v20
	v_mov_b32_e32 v28, v21
	v_mov_b32_e32 v27, v18
	v_mov_b32_e32 v26, v19
	v_mov_b32_e32 v25, v16
	v_mov_b32_e32 v24, v17
	v_mov_b32_e32 v23, v12
	v_mov_b32_e32 v22, v13
	v_mov_b32_e32 v21, v10
	v_mov_b32_e32 v20, v11
	v_mov_b32_e32 v19, v8
	v_mov_b32_e32 v18, v9
	v_mov_b32_e32 v17, v6
	v_mov_b32_e32 v16, v7
	s_waitcnt lgkmcnt(0)
	v_mov_b32_e32 v46, v57
	v_mov_b32_e32 v45, v42
	v_mov_b32_e32 v44, v43
	v_mov_b32_e32 v43, v40
	v_mov_b32_e32 v42, v41
	v_mov_b32_e32 v41, v38
	v_mov_b32_e32 v40, v39
	v_mov_b32_e32 v39, v36
	v_mov_b32_e32 v38, v37
	v_mov_b32_e32 v37, v34
	v_mov_b32_e32 v36, v35
	v_mov_b32_e32 v35, v32
	v_mov_b32_e32 v34, v33
	v_mov_b32_e32 v33, v14
	v_mov_b32_e32 v32, v15
	v_mov_b32_e32 v47, v56
